# P1 EpiAct epilogue rewritten with packed f32 VALU ops (same math), row scales read from LDS
# speedup vs baseline: 1.0648x; 1.0039x over previous
; __device__ __forceinline__ void row_rs8(const float* SS, int row0, int fq, float (&rsv)[2][4]) {
;     f32x4 q[2][4];
; #pragma unroll
;     for (int ai = 0; ai < 2; ++ai)
; #pragma unroll
;         for (int m = 0; m < 4; ++m) q[ai][m] = *(const f32x4*)(SS + (size_t)(row0 + ai * HALF + m * 16) * 16 + 4 * fq);
; #pragma unroll
;     for (int ai = 0; ai < 2; ++ai)
; #pragma unroll
;         for (int m = 0; m < 4; ++m) { float t = (q[ai][m][0] + q[ai][m][1]) + (q[ai][m][2] + q[ai][m][3]); t += __shfl_xor(t, 16); t += __shfl_xor(t, 32); rsv[ai][m] = __builtin_amdgcn_rsqf(t * (1.0f / 1024.0f) + 1e-6f); }
; }
;     __device__ __forceinline__ void operator()(const f32x4 (&acc)[2][2][4][2], const Unit& u, int wr, int wc, int fr, int fq) const {
;         const int row0 = u.pm * BM + wr * 64 + fr, col0 = u.pn * HALF + wc * 32 + 8 * fq;
;         float rsv[2][4]; row_rs8(SS, row0, fq, rsv);
; #pragma unroll
;         for (int ai = 0; ai < 2; ++ai)
; #pragma unroll
;             for (int m = 0; m < 4; ++m) {
;                 const int r = row0 + ai * HALF + m * 16; const float rs = rsv[ai][m], nrs = rs * -1.4426950408889634f, rs2 = rs * rs;
;                 float o[8];
; #pragma unroll
;                 for (int n = 0; n < 2; ++n) {
;                     const f32x4 t = acc[ai][0][m][n] * nrs, p = (acc[ai][0][m][n] * acc[ai][1][m][n]) * rs2;
.LBB0_267:
	v_lshl_add_u32 v162, s4, 8, v129
	v_and_b32_e32 v128, 48, v192
	v_lshl_add_u32 v128, v129, 6, v128
	v_add_u32_e32 v128, 0x20000, v128
	ds_read_b128 v[174:177], v128
	ds_read_b128 v[178:181], v128 offset:1024
	ds_read_b128 v[182:185], v128 offset:2048
	ds_read_b128 v[186:189], v128 offset:3072
	ds_read_b128 v[194:197], v128 offset:8192
	ds_read_b128 v[198:201], v128 offset:9216
	ds_read_b128 v[202:205], v128 offset:10240
	ds_read_b128 v[206:209], v128 offset:11264
	v_xor_b32_e32 v210, 16, v171
	v_xor_b32_e32 v211, 32, v171
	v_lshlrev_b32_e32 v210, 2, v210
	v_lshlrev_b32_e32 v211, 2, v211
	v_or_b32_e32 v160, 16, v162
	v_or_b32_e32 v158, 32, v162
	v_or_b32_e32 v156, 48, v162
	v_add_u32_e32 v154, 0x80, v162
	v_add_u32_e32 v152, 0x90, v162
	v_add_u32_e32 v150, 0xa0, v162
	v_add_u32_e32 v148, 0xb0, v162
	v_lshl_or_b32 v164, s5, 7, v167
	v_lshlrev_b32_e32 v164, 1, v164
	v_mov_b32_e32 v165, 0
	v_mov_b64_e32 v[220:221], s[52:53]
	s_and_b64 vcc, exec, s[6:7]
	s_mov_b64 s[6:7], -1
	v_pk_mul_f32 v[124:125], v[124:125], v[120:121]
	v_pk_mul_f32 v[126:127], v[126:127], v[122:123]
	v_pk_mul_f32 v[112:113], v[112:113], v[116:117]
	v_pk_mul_f32 v[114:115], v[114:115], v[118:119]
	v_pk_mul_f32 v[104:105], v[104:105], v[108:109]
	v_pk_mul_f32 v[106:107], v[106:107], v[110:111]
	v_pk_mul_f32 v[96:97], v[96:97], v[100:101]
	v_pk_mul_f32 v[98:99], v[98:99], v[102:103]
	v_pk_mul_f32 v[88:89], v[88:89], v[92:93]
	v_pk_mul_f32 v[90:91], v[90:91], v[94:95]
	v_pk_mul_f32 v[80:81], v[80:81], v[84:85]
	v_pk_mul_f32 v[82:83], v[82:83], v[86:87]
	v_pk_mul_f32 v[72:73], v[72:73], v[76:77]
	v_pk_mul_f32 v[74:75], v[74:75], v[78:79]
	v_pk_mul_f32 v[64:65], v[64:65], v[68:69]
	v_pk_mul_f32 v[66:67], v[66:67], v[70:71]
	v_pk_mul_f32 v[56:57], v[56:57], v[60:61]
	v_pk_mul_f32 v[58:59], v[58:59], v[62:63]
	v_pk_mul_f32 v[48:49], v[48:49], v[52:53]
	v_pk_mul_f32 v[50:51], v[50:51], v[54:55]
	v_pk_mul_f32 v[40:41], v[40:41], v[44:45]
	v_pk_mul_f32 v[42:43], v[42:43], v[46:47]
	v_pk_mul_f32 v[32:33], v[32:33], v[36:37]
	v_pk_mul_f32 v[34:35], v[34:35], v[38:39]
	v_pk_mul_f32 v[24:25], v[24:25], v[28:29]
	v_pk_mul_f32 v[26:27], v[26:27], v[30:31]
	v_pk_mul_f32 v[16:17], v[16:17], v[20:21]
	v_pk_mul_f32 v[18:19], v[18:19], v[22:23]
	v_pk_mul_f32 v[8:9], v[8:9], v[12:13]
	v_pk_mul_f32 v[10:11], v[10:11], v[14:15]
	v_pk_mul_f32 v[0:1], v[0:1], v[4:5]
	v_pk_mul_f32 v[2:3], v[2:3], v[6:7]
	s_waitcnt lgkmcnt(0)
	v_pk_add_f32 v[174:175], v[174:175], v[176:177]
	v_pk_add_f32 v[178:179], v[178:179], v[180:181]
	v_pk_add_f32 v[182:183], v[182:183], v[184:185]
	v_pk_add_f32 v[186:187], v[186:187], v[188:189]
	v_pk_add_f32 v[194:195], v[194:195], v[196:197]
	v_pk_add_f32 v[198:199], v[198:199], v[200:201]
	v_pk_add_f32 v[202:203], v[202:203], v[204:205]
	v_pk_add_f32 v[206:207], v[206:207], v[208:209]
	v_add_f32_e32 v212, v174, v175
	v_add_f32_e32 v213, v178, v179
	v_add_f32_e32 v214, v182, v183
	v_add_f32_e32 v215, v186, v187
	v_add_f32_e32 v216, v194, v195
	v_add_f32_e32 v217, v198, v199
	v_add_f32_e32 v218, v202, v203
	v_add_f32_e32 v219, v206, v207
	ds_bpermute_b32 v222, v210, v212
	ds_bpermute_b32 v223, v210, v213
	ds_bpermute_b32 v224, v210, v214
	ds_bpermute_b32 v225, v210, v215
	ds_bpermute_b32 v226, v210, v216
	ds_bpermute_b32 v227, v210, v217
	ds_bpermute_b32 v228, v210, v218
	ds_bpermute_b32 v229, v210, v219
	s_waitcnt lgkmcnt(7)
	v_add_f32_e32 v212, v212, v222
	s_waitcnt lgkmcnt(6)
	v_add_f32_e32 v213, v213, v223
	s_waitcnt lgkmcnt(5)
	v_add_f32_e32 v214, v214, v224
	s_waitcnt lgkmcnt(4)
	v_add_f32_e32 v215, v215, v225
	s_waitcnt lgkmcnt(3)
	v_add_f32_e32 v216, v216, v226
	s_waitcnt lgkmcnt(2)
	v_add_f32_e32 v217, v217, v227
	s_waitcnt lgkmcnt(1)
	v_add_f32_e32 v218, v218, v228
	s_waitcnt lgkmcnt(0)
	v_add_f32_e32 v219, v219, v229
	ds_bpermute_b32 v222, v211, v212
	ds_bpermute_b32 v223, v211, v213
	ds_bpermute_b32 v224, v211, v214
	ds_bpermute_b32 v225, v211, v215
	ds_bpermute_b32 v226, v211, v216
	ds_bpermute_b32 v227, v211, v217
	ds_bpermute_b32 v228, v211, v218
	ds_bpermute_b32 v229, v211, v219
	s_waitcnt lgkmcnt(7)
	v_add_f32_e32 v212, v212, v222
	s_waitcnt lgkmcnt(6)
	v_add_f32_e32 v213, v213, v223
	s_waitcnt lgkmcnt(5)
	v_add_f32_e32 v214, v214, v224
	s_waitcnt lgkmcnt(4)
	v_add_f32_e32 v215, v215, v225
	s_waitcnt lgkmcnt(3)
	v_add_f32_e32 v216, v216, v226
	s_waitcnt lgkmcnt(2)
	v_add_f32_e32 v217, v217, v227
	s_waitcnt lgkmcnt(1)
	v_add_f32_e32 v218, v218, v228
	s_waitcnt lgkmcnt(0)
; __device__ __forceinline__ unsigned cvt_pk_bf16(float lo, float hi) { unsigned r; asm volatile("v_cvt_pk_bf16_f32 %0, %1, %2" : "=v"(r) : "v"(lo), "v"(hi)); return r; }
; __device__ __forceinline__ float fast_rcp(float x) { return __builtin_amdgcn_rcpf(x); }
; __device__ __forceinline__ unsigned cvt_pk_bf16(float lo, float hi) { const f32x2 v = {lo, hi}; const bf16x2_t b = __builtin_convertvector(v, bf16x2_t); return __builtin_bit_cast(unsigned, b); }
; __device__ __forceinline__ void row_rs8(const float* SS, int row0, int fq, float (&rsv)[2][4]) {
;     ...
;         for (int m = 0; m < 4; ++m) { float t = (q[ai][m][0] + q[ai][m][1]) + (q[ai][m][2] + q[ai][m][3]); t += __shfl_xor(t, 16); t += __shfl_xor(t, 32); rsv[ai][m] = __builtin_amdgcn_rsqf(t * (1.0f / 1024.0f) + 1e-6f); }
;     __device__ __forceinline__ void operator()(const f32x4 (&acc)[2][2][4][2], const Unit& u, int wr, int wc, int fr, int fq) const {
;     ...
;                 const int r = row0 + ai * HALF + m * 16; const float rs = rsv[ai][m], nrs = rs * -1.4426950408889634f, rs2 = rs * rs;
;                 float o[8];
; #pragma unroll
;                 for (int n = 0; n < 2; ++n) {
;                     const f32x4 t = acc[ai][0][m][n] * nrs, p = (acc[ai][0][m][n] * acc[ai][1][m][n]) * rs2;
; #pragma unroll
;                     for (int j = 0; j < 4; ++j) o[4 * n + j] = p[j] * fast_rcp(1.0f + __builtin_amdgcn_exp2f(t[j]));
;                 }
;                 u32x4 w; w.x = cvt_pk_bf16(o[0], o[1]); w.y = cvt_pk_bf16(o[2], o[3]); w.z = cvt_pk_bf16(o[4], o[5]); w.w = cvt_pk_bf16(o[6], o[7]);
;                 *(u32x4*)(O + (size_t)r * ldo + col0) = w;
	v_add_f32_e32 v219, v219, v229
	v_fmamk_f32 v212, v212, 0x3a800000, v172
	v_fmamk_f32 v213, v213, 0x3a800000, v172
	v_fmamk_f32 v214, v214, 0x3a800000, v172
	v_fmamk_f32 v215, v215, 0x3a800000, v172
	v_fmamk_f32 v216, v216, 0x3a800000, v172
	v_fmamk_f32 v217, v217, 0x3a800000, v172
	v_fmamk_f32 v218, v218, 0x3a800000, v172
	v_fmamk_f32 v219, v219, 0x3a800000, v172
	v_rsq_f32_e32 v212, v212
	v_rsq_f32_e32 v213, v213
	v_rsq_f32_e32 v214, v214
	v_rsq_f32_e32 v215, v215
	v_rsq_f32_e32 v216, v216
	v_rsq_f32_e32 v217, v217
	v_rsq_f32_e32 v218, v218
	v_rsq_f32_e32 v219, v219
	v_mul_f32_e32 v230, 0xbfb8aa3b, v212
	v_mul_f32_e32 v231, v212, v212
	v_mul_f32_e32 v232, 0xbfb8aa3b, v213
	v_mul_f32_e32 v233, v213, v213
	v_mul_f32_e32 v234, 0xbfb8aa3b, v214
	v_mul_f32_e32 v235, v214, v214
	v_mul_f32_e32 v184, 0xbfb8aa3b, v215
	v_mul_f32_e32 v185, v215, v215
	v_mul_f32_e32 v186, 0xbfb8aa3b, v216
	v_mul_f32_e32 v187, v216, v216
	v_mul_f32_e32 v188, 0xbfb8aa3b, v217
	v_mul_f32_e32 v189, v217, v217
	v_mul_f32_e32 v190, 0xbfb8aa3b, v218
	v_mul_f32_e32 v191, v218, v218
	v_mul_f32_e32 v204, 0xbfb8aa3b, v219
	v_mul_f32_e32 v205, v219, v219
	v_pk_mul_f32 v[120:121], v[120:121], v[230:231] op_sel_hi:[1,0]
	v_pk_mul_f32 v[122:123], v[122:123], v[230:231] op_sel_hi:[1,0]
	v_pk_mul_f32 v[116:117], v[116:117], v[230:231] op_sel_hi:[1,0]
	v_pk_mul_f32 v[118:119], v[118:119], v[230:231] op_sel_hi:[1,0]
	v_exp_f32_e32 v120, v120
	v_exp_f32_e32 v121, v121
	v_exp_f32_e32 v122, v122
	v_exp_f32_e32 v123, v123
	v_exp_f32_e32 v116, v116
	v_exp_f32_e32 v117, v117
	v_exp_f32_e32 v118, v118
	v_exp_f32_e32 v119, v119
	v_pk_mul_f32 v[124:125], v[124:125], v[230:231] op_sel:[0,1] op_sel_hi:[1,1]
	v_pk_mul_f32 v[126:127], v[126:127], v[230:231] op_sel:[0,1] op_sel_hi:[1,1]
	v_pk_mul_f32 v[112:113], v[112:113], v[230:231] op_sel:[0,1] op_sel_hi:[1,1]
	v_pk_mul_f32 v[114:115], v[114:115], v[230:231] op_sel:[0,1] op_sel_hi:[1,1]
	v_pk_add_f32 v[120:121], v[120:121], 1.0 op_sel_hi:[1,0]
	v_pk_add_f32 v[122:123], v[122:123], 1.0 op_sel_hi:[1,0]
	v_pk_add_f32 v[116:117], v[116:117], 1.0 op_sel_hi:[1,0]
	v_pk_add_f32 v[118:119], v[118:119], 1.0 op_sel_hi:[1,0]
	v_rcp_f32_e32 v120, v120
	v_rcp_f32_e32 v121, v121
	v_rcp_f32_e32 v122, v122
	v_rcp_f32_e32 v123, v123
	v_rcp_f32_e32 v116, v116
	v_rcp_f32_e32 v117, v117
	v_rcp_f32_e32 v118, v118
	v_rcp_f32_e32 v119, v119
	v_mad_i64_i32 v[208:209], s[4:5], v162, s68, v[220:221]
	v_lshl_add_u64 v[208:209], v[208:209], 0, v[164:165]
	v_pk_mul_f32 v[124:125], v[124:125], v[120:121]
	v_pk_mul_f32 v[126:127], v[126:127], v[122:123]
	v_pk_mul_f32 v[112:113], v[112:113], v[116:117]
	v_pk_mul_f32 v[114:115], v[114:115], v[118:119]
	v_cvt_pk_bf16_f32 v120, v124, v125
	v_cvt_pk_bf16_f32 v121, v126, v127
	v_cvt_pk_bf16_f32 v122, v112, v113
	v_cvt_pk_bf16_f32 v123, v114, v115
	global_store_dwordx4 v[208:209], v[120:123], off
	v_pk_mul_f32 v[108:109], v[108:109], v[232:233] op_sel_hi:[1,0]
	v_pk_mul_f32 v[110:111], v[110:111], v[232:233] op_sel_hi:[1,0]
	v_pk_mul_f32 v[100:101], v[100:101], v[232:233] op_sel_hi:[1,0]
	v_pk_mul_f32 v[102:103], v[102:103], v[232:233] op_sel_hi:[1,0]
	v_exp_f32_e32 v108, v108
	v_exp_f32_e32 v109, v109
	v_exp_f32_e32 v110, v110
	v_exp_f32_e32 v111, v111
	v_exp_f32_e32 v100, v100
	v_exp_f32_e32 v101, v101
	v_exp_f32_e32 v102, v102
	v_exp_f32_e32 v103, v103
	v_pk_mul_f32 v[104:105], v[104:105], v[232:233] op_sel:[0,1] op_sel_hi:[1,1]
	v_pk_mul_f32 v[106:107], v[106:107], v[232:233] op_sel:[0,1] op_sel_hi:[1,1]
	v_pk_mul_f32 v[96:97], v[96:97], v[232:233] op_sel:[0,1] op_sel_hi:[1,1]
	v_pk_mul_f32 v[98:99], v[98:99], v[232:233] op_sel:[0,1] op_sel_hi:[1,1]
	v_pk_add_f32 v[108:109], v[108:109], 1.0 op_sel_hi:[1,0]
	v_pk_add_f32 v[110:111], v[110:111], 1.0 op_sel_hi:[1,0]
	v_pk_add_f32 v[100:101], v[100:101], 1.0 op_sel_hi:[1,0]
	v_pk_add_f32 v[102:103], v[102:103], 1.0 op_sel_hi:[1,0]
	v_rcp_f32_e32 v108, v108
	v_rcp_f32_e32 v109, v109
	v_rcp_f32_e32 v110, v110
	v_rcp_f32_e32 v111, v111
	v_rcp_f32_e32 v100, v100
	v_rcp_f32_e32 v101, v101
	v_rcp_f32_e32 v102, v102
	v_rcp_f32_e32 v103, v103
	v_mad_i64_i32 v[208:209], s[4:5], v160, s68, v[220:221]
	v_lshl_add_u64 v[208:209], v[208:209], 0, v[164:165]
	v_pk_mul_f32 v[104:105], v[104:105], v[108:109]
	v_pk_mul_f32 v[106:107], v[106:107], v[110:111]
	v_pk_mul_f32 v[96:97], v[96:97], v[100:101]
	v_pk_mul_f32 v[98:99], v[98:99], v[102:103]
	v_cvt_pk_bf16_f32 v108, v104, v105
	v_cvt_pk_bf16_f32 v109, v106, v107
	v_cvt_pk_bf16_f32 v110, v96, v97
	v_cvt_pk_bf16_f32 v111, v98, v99
	global_store_dwordx4 v[208:209], v[108:111], off
	v_pk_mul_f32 v[92:93], v[92:93], v[234:235] op_sel_hi:[1,0]
	v_pk_mul_f32 v[94:95], v[94:95], v[234:235] op_sel_hi:[1,0]
	v_pk_mul_f32 v[84:85], v[84:85], v[234:235] op_sel_hi:[1,0]
	v_pk_mul_f32 v[86:87], v[86:87], v[234:235] op_sel_hi:[1,0]
	v_exp_f32_e32 v92, v92
	v_exp_f32_e32 v93, v93
	v_exp_f32_e32 v94, v94
	v_exp_f32_e32 v95, v95
	v_exp_f32_e32 v84, v84
	v_exp_f32_e32 v85, v85
	v_exp_f32_e32 v86, v86
	v_exp_f32_e32 v87, v87
	v_pk_mul_f32 v[88:89], v[88:89], v[234:235] op_sel:[0,1] op_sel_hi:[1,1]
	v_pk_mul_f32 v[90:91], v[90:91], v[234:235] op_sel:[0,1] op_sel_hi:[1,1]
	v_pk_mul_f32 v[80:81], v[80:81], v[234:235] op_sel:[0,1] op_sel_hi:[1,1]
	v_pk_mul_f32 v[82:83], v[82:83], v[234:235] op_sel:[0,1] op_sel_hi:[1,1]
	v_pk_add_f32 v[92:93], v[92:93], 1.0 op_sel_hi:[1,0]
	v_pk_add_f32 v[94:95], v[94:95], 1.0 op_sel_hi:[1,0]
	v_pk_add_f32 v[84:85], v[84:85], 1.0 op_sel_hi:[1,0]
	v_pk_add_f32 v[86:87], v[86:87], 1.0 op_sel_hi:[1,0]
	v_rcp_f32_e32 v92, v92
	v_rcp_f32_e32 v93, v93
	v_rcp_f32_e32 v94, v94
	v_rcp_f32_e32 v95, v95
	v_rcp_f32_e32 v84, v84
	v_rcp_f32_e32 v85, v85
; __device__ __forceinline__ unsigned cvt_pk_bf16(float lo, float hi) { unsigned r; asm volatile("v_cvt_pk_bf16_f32 %0, %1, %2" : "=v"(r) : "v"(lo), "v"(hi)); return r; }
; __device__ __forceinline__ float fast_rcp(float x) { return __builtin_amdgcn_rcpf(x); }
; __device__ __forceinline__ unsigned cvt_pk_bf16(float lo, float hi) { const f32x2 v = {lo, hi}; const bf16x2_t b = __builtin_convertvector(v, bf16x2_t); return __builtin_bit_cast(unsigned, b); }
;     __device__ __forceinline__ void operator()(const f32x4 (&acc)[2][2][4][2], const Unit& u, int wr, int wc, int fr, int fq) const {
;     ...
;             for (int m = 0; m < 4; ++m) {
;                 const int r = row0 + ai * HALF + m * 16; const float rs = rsv[ai][m], nrs = rs * -1.4426950408889634f, rs2 = rs * rs;
;                 float o[8];
; #pragma unroll
;                 for (int n = 0; n < 2; ++n) {
;                     const f32x4 t = acc[ai][0][m][n] * nrs, p = (acc[ai][0][m][n] * acc[ai][1][m][n]) * rs2;
; #pragma unroll
;                     for (int j = 0; j < 4; ++j) o[4 * n + j] = p[j] * fast_rcp(1.0f + __builtin_amdgcn_exp2f(t[j]));
;                 }
;                 u32x4 w; w.x = cvt_pk_bf16(o[0], o[1]); w.y = cvt_pk_bf16(o[2], o[3]); w.z = cvt_pk_bf16(o[4], o[5]); w.w = cvt_pk_bf16(o[6], o[7]);
;                 *(u32x4*)(O + (size_t)r * ldo + col0) = w;
	v_rcp_f32_e32 v86, v86
	v_rcp_f32_e32 v87, v87
	v_mad_i64_i32 v[208:209], s[4:5], v158, s68, v[220:221]
	v_lshl_add_u64 v[208:209], v[208:209], 0, v[164:165]
	v_pk_mul_f32 v[88:89], v[88:89], v[92:93]
	v_pk_mul_f32 v[90:91], v[90:91], v[94:95]
	v_pk_mul_f32 v[80:81], v[80:81], v[84:85]
	v_pk_mul_f32 v[82:83], v[82:83], v[86:87]
	v_cvt_pk_bf16_f32 v92, v88, v89
	v_cvt_pk_bf16_f32 v93, v90, v91
	v_cvt_pk_bf16_f32 v94, v80, v81
	v_cvt_pk_bf16_f32 v95, v82, v83
	global_store_dwordx4 v[208:209], v[92:95], off
	v_pk_mul_f32 v[76:77], v[76:77], v[184:185] op_sel_hi:[1,0]
	v_pk_mul_f32 v[78:79], v[78:79], v[184:185] op_sel_hi:[1,0]
	v_pk_mul_f32 v[68:69], v[68:69], v[184:185] op_sel_hi:[1,0]
	v_pk_mul_f32 v[70:71], v[70:71], v[184:185] op_sel_hi:[1,0]
	v_exp_f32_e32 v76, v76
	v_exp_f32_e32 v77, v77
	v_exp_f32_e32 v78, v78
	v_exp_f32_e32 v79, v79
	v_exp_f32_e32 v68, v68
	v_exp_f32_e32 v69, v69
	v_exp_f32_e32 v70, v70
	v_exp_f32_e32 v71, v71
	v_pk_mul_f32 v[72:73], v[72:73], v[184:185] op_sel:[0,1] op_sel_hi:[1,1]
	v_pk_mul_f32 v[74:75], v[74:75], v[184:185] op_sel:[0,1] op_sel_hi:[1,1]
	v_pk_mul_f32 v[64:65], v[64:65], v[184:185] op_sel:[0,1] op_sel_hi:[1,1]
	v_pk_mul_f32 v[66:67], v[66:67], v[184:185] op_sel:[0,1] op_sel_hi:[1,1]
	v_pk_add_f32 v[76:77], v[76:77], 1.0 op_sel_hi:[1,0]
	v_pk_add_f32 v[78:79], v[78:79], 1.0 op_sel_hi:[1,0]
	v_pk_add_f32 v[68:69], v[68:69], 1.0 op_sel_hi:[1,0]
	v_pk_add_f32 v[70:71], v[70:71], 1.0 op_sel_hi:[1,0]
	v_rcp_f32_e32 v76, v76
	v_rcp_f32_e32 v77, v77
	v_rcp_f32_e32 v78, v78
	v_rcp_f32_e32 v79, v79
	v_rcp_f32_e32 v68, v68
	v_rcp_f32_e32 v69, v69
	v_rcp_f32_e32 v70, v70
	v_rcp_f32_e32 v71, v71
	v_mad_i64_i32 v[208:209], s[4:5], v156, s68, v[220:221]
	v_lshl_add_u64 v[208:209], v[208:209], 0, v[164:165]
	v_pk_mul_f32 v[72:73], v[72:73], v[76:77]
	v_pk_mul_f32 v[74:75], v[74:75], v[78:79]
	v_pk_mul_f32 v[64:65], v[64:65], v[68:69]
	v_pk_mul_f32 v[66:67], v[66:67], v[70:71]
	v_cvt_pk_bf16_f32 v76, v72, v73
	v_cvt_pk_bf16_f32 v77, v74, v75
	v_cvt_pk_bf16_f32 v78, v64, v65
	v_cvt_pk_bf16_f32 v79, v66, v67
	global_store_dwordx4 v[208:209], v[76:79], off
	v_pk_mul_f32 v[60:61], v[60:61], v[186:187] op_sel_hi:[1,0]
	v_pk_mul_f32 v[62:63], v[62:63], v[186:187] op_sel_hi:[1,0]
	v_pk_mul_f32 v[52:53], v[52:53], v[186:187] op_sel_hi:[1,0]
	v_pk_mul_f32 v[54:55], v[54:55], v[186:187] op_sel_hi:[1,0]
	v_exp_f32_e32 v60, v60
	v_exp_f32_e32 v61, v61
	v_exp_f32_e32 v62, v62
	v_exp_f32_e32 v63, v63
	v_exp_f32_e32 v52, v52
	v_exp_f32_e32 v53, v53
	v_exp_f32_e32 v54, v54
	v_exp_f32_e32 v55, v55
	v_pk_mul_f32 v[56:57], v[56:57], v[186:187] op_sel:[0,1] op_sel_hi:[1,1]
	v_pk_mul_f32 v[58:59], v[58:59], v[186:187] op_sel:[0,1] op_sel_hi:[1,1]
	v_pk_mul_f32 v[48:49], v[48:49], v[186:187] op_sel:[0,1] op_sel_hi:[1,1]
	v_pk_mul_f32 v[50:51], v[50:51], v[186:187] op_sel:[0,1] op_sel_hi:[1,1]
	v_pk_add_f32 v[60:61], v[60:61], 1.0 op_sel_hi:[1,0]
	v_pk_add_f32 v[62:63], v[62:63], 1.0 op_sel_hi:[1,0]
	v_pk_add_f32 v[52:53], v[52:53], 1.0 op_sel_hi:[1,0]
	v_pk_add_f32 v[54:55], v[54:55], 1.0 op_sel_hi:[1,0]
	v_rcp_f32_e32 v60, v60
	v_rcp_f32_e32 v61, v61
	v_rcp_f32_e32 v62, v62
	v_rcp_f32_e32 v63, v63
	v_rcp_f32_e32 v52, v52
	v_rcp_f32_e32 v53, v53
	v_rcp_f32_e32 v54, v54
	v_rcp_f32_e32 v55, v55
	v_mad_i64_i32 v[208:209], s[4:5], v154, s68, v[220:221]
	v_lshl_add_u64 v[208:209], v[208:209], 0, v[164:165]
	v_pk_mul_f32 v[56:57], v[56:57], v[60:61]
	v_pk_mul_f32 v[58:59], v[58:59], v[62:63]
	v_pk_mul_f32 v[48:49], v[48:49], v[52:53]
	v_pk_mul_f32 v[50:51], v[50:51], v[54:55]
	v_cvt_pk_bf16_f32 v60, v56, v57
	v_cvt_pk_bf16_f32 v61, v58, v59
	v_cvt_pk_bf16_f32 v62, v48, v49
	v_cvt_pk_bf16_f32 v63, v50, v51
	global_store_dwordx4 v[208:209], v[60:63], off
	v_pk_mul_f32 v[44:45], v[44:45], v[188:189] op_sel_hi:[1,0]
	v_pk_mul_f32 v[46:47], v[46:47], v[188:189] op_sel_hi:[1,0]
	v_pk_mul_f32 v[36:37], v[36:37], v[188:189] op_sel_hi:[1,0]
	v_pk_mul_f32 v[38:39], v[38:39], v[188:189] op_sel_hi:[1,0]
	v_exp_f32_e32 v44, v44
	v_exp_f32_e32 v45, v45
	v_exp_f32_e32 v46, v46
	v_exp_f32_e32 v47, v47
	v_exp_f32_e32 v36, v36
	v_exp_f32_e32 v37, v37
	v_exp_f32_e32 v38, v38
	v_exp_f32_e32 v39, v39
	v_pk_mul_f32 v[40:41], v[40:41], v[188:189] op_sel:[0,1] op_sel_hi:[1,1]
	v_pk_mul_f32 v[42:43], v[42:43], v[188:189] op_sel:[0,1] op_sel_hi:[1,1]
; __device__ __forceinline__ unsigned cvt_pk_bf16(float lo, float hi) { unsigned r; asm volatile("v_cvt_pk_bf16_f32 %0, %1, %2" : "=v"(r) : "v"(lo), "v"(hi)); return r; }
; __device__ __forceinline__ float fast_rcp(float x) { return __builtin_amdgcn_rcpf(x); }
; #define PG8_BAR __builtin_amdgcn_s_barrier()
; __device__ __forceinline__ unsigned cvt_pk_bf16(float lo, float hi) { const f32x2 v = {lo, hi}; const bf16x2_t b = __builtin_convertvector(v, bf16x2_t); return __builtin_bit_cast(unsigned, b); }
;     __device__ __forceinline__ void operator()(const f32x4 (&acc)[2][2][4][2], const Unit& u, int wr, int wc, int fr, int fq) const {
;     ...
;             for (int m = 0; m < 4; ++m) {
;                 const int r = row0 + ai * HALF + m * 16; const float rs = rsv[ai][m], nrs = rs * -1.4426950408889634f, rs2 = rs * rs;
;                 float o[8];
; #pragma unroll
;                 for (int n = 0; n < 2; ++n) {
;                     const f32x4 t = acc[ai][0][m][n] * nrs, p = (acc[ai][0][m][n] * acc[ai][1][m][n]) * rs2;
; #pragma unroll
;                     for (int j = 0; j < 4; ++j) o[4 * n + j] = p[j] * fast_rcp(1.0f + __builtin_amdgcn_exp2f(t[j]));
;                 }
;                 u32x4 w; w.x = cvt_pk_bf16(o[0], o[1]); w.y = cvt_pk_bf16(o[2], o[3]); w.z = cvt_pk_bf16(o[4], o[5]); w.w = cvt_pk_bf16(o[6], o[7]);
;                 *(u32x4*)(O + (size_t)r * ldo + col0) = w;
; template <class Epi, class Sched, bool ALIGN_EPI = false, bool SP2 = false>
; __device__ __forceinline__ void gemm_phase(PG8_LAS unsigned char* lds, const Gemm g, const Sched& S, const Epi& E) {
;     ...
;         if (!has_next) break;
; #pragma unroll
;         for (int a = 0; a < 2; ++a)
; #pragma unroll
;             for (int b = 0; b < 2; ++b)
; #pragma unroll
;                 for (int m = 0; m < 4; ++m)
; #pragma unroll
;                     for (int n = 0; n < 2; ++n) acc[a][b][m][n] = (f32x4){0.f, 0.f, 0.f, 0.f};
;         cur = nxt; cA = nA; cB = nB; ++ui;
;         if constexpr (ALIGN_EPI) { if (wr == 1) PG8_BAR; }
	v_pk_mul_f32 v[32:33], v[32:33], v[188:189] op_sel:[0,1] op_sel_hi:[1,1]
	v_pk_mul_f32 v[34:35], v[34:35], v[188:189] op_sel:[0,1] op_sel_hi:[1,1]
	v_pk_add_f32 v[44:45], v[44:45], 1.0 op_sel_hi:[1,0]
	v_pk_add_f32 v[46:47], v[46:47], 1.0 op_sel_hi:[1,0]
	v_pk_add_f32 v[36:37], v[36:37], 1.0 op_sel_hi:[1,0]
	v_pk_add_f32 v[38:39], v[38:39], 1.0 op_sel_hi:[1,0]
	v_rcp_f32_e32 v44, v44
	v_rcp_f32_e32 v45, v45
	v_rcp_f32_e32 v46, v46
	v_rcp_f32_e32 v47, v47
	v_rcp_f32_e32 v36, v36
	v_rcp_f32_e32 v37, v37
	v_rcp_f32_e32 v38, v38
	v_rcp_f32_e32 v39, v39
	v_mad_i64_i32 v[208:209], s[4:5], v152, s68, v[220:221]
	v_lshl_add_u64 v[208:209], v[208:209], 0, v[164:165]
	v_pk_mul_f32 v[40:41], v[40:41], v[44:45]
	v_pk_mul_f32 v[42:43], v[42:43], v[46:47]
	v_pk_mul_f32 v[32:33], v[32:33], v[36:37]
	v_pk_mul_f32 v[34:35], v[34:35], v[38:39]
	v_cvt_pk_bf16_f32 v44, v40, v41
	v_cvt_pk_bf16_f32 v45, v42, v43
	v_cvt_pk_bf16_f32 v46, v32, v33
	v_cvt_pk_bf16_f32 v47, v34, v35
	global_store_dwordx4 v[208:209], v[44:47], off
	v_pk_mul_f32 v[28:29], v[28:29], v[190:191] op_sel_hi:[1,0]
	v_pk_mul_f32 v[30:31], v[30:31], v[190:191] op_sel_hi:[1,0]
	v_pk_mul_f32 v[20:21], v[20:21], v[190:191] op_sel_hi:[1,0]
	v_pk_mul_f32 v[22:23], v[22:23], v[190:191] op_sel_hi:[1,0]
	v_exp_f32_e32 v28, v28
	v_exp_f32_e32 v29, v29
	v_exp_f32_e32 v30, v30
	v_exp_f32_e32 v31, v31
	v_exp_f32_e32 v20, v20
	v_exp_f32_e32 v21, v21
	v_exp_f32_e32 v22, v22
	v_exp_f32_e32 v23, v23
	v_pk_mul_f32 v[24:25], v[24:25], v[190:191] op_sel:[0,1] op_sel_hi:[1,1]
	v_pk_mul_f32 v[26:27], v[26:27], v[190:191] op_sel:[0,1] op_sel_hi:[1,1]
	v_pk_mul_f32 v[16:17], v[16:17], v[190:191] op_sel:[0,1] op_sel_hi:[1,1]
	v_pk_mul_f32 v[18:19], v[18:19], v[190:191] op_sel:[0,1] op_sel_hi:[1,1]
	v_pk_add_f32 v[28:29], v[28:29], 1.0 op_sel_hi:[1,0]
	v_pk_add_f32 v[30:31], v[30:31], 1.0 op_sel_hi:[1,0]
	v_pk_add_f32 v[20:21], v[20:21], 1.0 op_sel_hi:[1,0]
	v_pk_add_f32 v[22:23], v[22:23], 1.0 op_sel_hi:[1,0]
	v_rcp_f32_e32 v28, v28
	v_rcp_f32_e32 v29, v29
	v_rcp_f32_e32 v30, v30
	v_rcp_f32_e32 v31, v31
	v_rcp_f32_e32 v20, v20
	v_rcp_f32_e32 v21, v21
	v_rcp_f32_e32 v22, v22
	v_rcp_f32_e32 v23, v23
	v_mad_i64_i32 v[208:209], s[4:5], v150, s68, v[220:221]
	v_lshl_add_u64 v[208:209], v[208:209], 0, v[164:165]
	v_pk_mul_f32 v[24:25], v[24:25], v[28:29]
	v_pk_mul_f32 v[26:27], v[26:27], v[30:31]
	v_pk_mul_f32 v[16:17], v[16:17], v[20:21]
	v_pk_mul_f32 v[18:19], v[18:19], v[22:23]
	v_cvt_pk_bf16_f32 v28, v24, v25
	v_cvt_pk_bf16_f32 v29, v26, v27
	v_cvt_pk_bf16_f32 v30, v16, v17
	v_cvt_pk_bf16_f32 v31, v18, v19
	global_store_dwordx4 v[208:209], v[28:31], off
	v_pk_mul_f32 v[12:13], v[12:13], v[204:205] op_sel_hi:[1,0]
	v_pk_mul_f32 v[14:15], v[14:15], v[204:205] op_sel_hi:[1,0]
	v_pk_mul_f32 v[4:5], v[4:5], v[204:205] op_sel_hi:[1,0]
	v_pk_mul_f32 v[6:7], v[6:7], v[204:205] op_sel_hi:[1,0]
	v_exp_f32_e32 v12, v12
	v_exp_f32_e32 v13, v13
	v_exp_f32_e32 v14, v14
	v_exp_f32_e32 v15, v15
	v_exp_f32_e32 v4, v4
	v_exp_f32_e32 v5, v5
	v_exp_f32_e32 v6, v6
	v_exp_f32_e32 v7, v7
	v_pk_mul_f32 v[8:9], v[8:9], v[204:205] op_sel:[0,1] op_sel_hi:[1,1]
	v_pk_mul_f32 v[10:11], v[10:11], v[204:205] op_sel:[0,1] op_sel_hi:[1,1]
	v_pk_mul_f32 v[0:1], v[0:1], v[204:205] op_sel:[0,1] op_sel_hi:[1,1]
	v_pk_mul_f32 v[2:3], v[2:3], v[204:205] op_sel:[0,1] op_sel_hi:[1,1]
	v_pk_add_f32 v[12:13], v[12:13], 1.0 op_sel_hi:[1,0]
	v_pk_add_f32 v[14:15], v[14:15], 1.0 op_sel_hi:[1,0]
	v_pk_add_f32 v[4:5], v[4:5], 1.0 op_sel_hi:[1,0]
	v_pk_add_f32 v[6:7], v[6:7], 1.0 op_sel_hi:[1,0]
	v_rcp_f32_e32 v12, v12
	v_rcp_f32_e32 v13, v13
	v_rcp_f32_e32 v14, v14
	v_rcp_f32_e32 v15, v15
	v_rcp_f32_e32 v4, v4
	v_rcp_f32_e32 v5, v5
	v_rcp_f32_e32 v6, v6
	v_rcp_f32_e32 v7, v7
	v_mad_i64_i32 v[208:209], s[4:5], v148, s68, v[220:221]
	v_lshl_add_u64 v[208:209], v[208:209], 0, v[164:165]
	v_pk_mul_f32 v[8:9], v[8:9], v[12:13]
	v_pk_mul_f32 v[10:11], v[10:11], v[14:15]
	v_pk_mul_f32 v[0:1], v[0:1], v[4:5]
	v_pk_mul_f32 v[2:3], v[2:3], v[6:7]
	v_cvt_pk_bf16_f32 v12, v8, v9
	v_cvt_pk_bf16_f32 v13, v10, v11
	v_cvt_pk_bf16_f32 v14, v0, v1
	v_cvt_pk_bf16_f32 v15, v2, v3
	global_store_dwordx4 v[208:209], v[12:15], off
	s_cbranch_vccnz .LBB0_255
	s_andn2_b64 vcc, exec, s[16:17]
	s_cbranch_vccnz .LBB0_254
	s_barrier
	s_branch .LBB0_254
